# GEMM-up epilogue prologue de-serialisation: conv weight loads issued right after the last K-tail MFMA into dead fragment registers
# speedup vs baseline: 1.0093x; 1.0009x over previous
; #define STAGE(P, BASE, br, kt) STAGET(tid_, P, BASE, br, kt)
; #define LDA(dst, b, h) UFOR(m, 4) UFOR(k, 2) \
;     dst[m][k] = *reinterpret_cast<const bf16x8*>((char*)SA(b, h) + lds_byte(wr * 64 + m * 16 + fr, k * 32 + fq * 8))
; #define LDB(dst, b, h) UFOR(n, 2) UFOR(k, 2) \
;     dst[n][k] = *reinterpret_cast<const bf16x8*>((char*)SB(b, h) + lds_byte(wc * 32 + n * 16 + fr, k * 32 + fq * 8))
; #define MMA(ai, bj, At, Bq) do { __builtin_amdgcn_s_setprio(1); \
;     UFOR(m, 4) UFOR(n, 2) UFOR(k, 2) \
;       acc[ai][bj][m][n] = __builtin_amdgcn_mfma_f32_16x16x32_bf16(Bq[n][k], At[m][k], acc[ai][bj][m][n], 0, 0, 0); \
;     __builtin_amdgcn_s_setprio(0); } while (0)
; #define WAIT_V(n) asm volatile("s_waitcnt vmcnt(" #n ")" ::: "memory")
; #define WAIT_L(n) asm volatile("s_waitcnt lgkmcnt(" #n ")" ::: "memory")
; #define BAR __builtin_amdgcn_s_barrier()
; #define SCHED __builtin_amdgcn_sched_barrier(0)
; template <int EPI, int K, int KL> ...
;     ...
;     LDB(B0, 0, 0); SCHED; LDA(At, 0, 0); STAGE(SA(1, 1), A, brow + HALF, t + 1);
;     WAIT_L(8); BAR; WAIT_L(0); MMA(0, 0, At, B0); BAR; SCHED;
;     LDB(B1, 0, 1); STAGE(SB(0, 0), Bt, bcol, t + 2);
;     BAR; WAIT_L(0); MMA(0, 1, At, B1); BAR;
;     LDA(At, 0, 1); STAGE(SA(0, 0), A, brow, t + 2);
;     BAR; WAIT_L(0); MMA(1, 0, At, B0); BAR; SCHED;
;     STAGE(SB(0, 1), Bt, bcol + HALF, t + 2);
;     WAIT_V(6); BAR; MMA(1, 1, At, B1); BAR;
;     LDB(B0, 1, 0); SCHED; LDA(At, 1, 0); STAGE(SA(0, 1), A, brow + HALF, t + 2);
;     WAIT_L(8); BAR; WAIT_L(0); MMA(0, 0, At, B0); BAR; SCHED;
.LBB0_1107:
	ds_read_b128 v[136:139], v171
	ds_read_b128 v[174:177], v171 offset:1024
	ds_read_b128 v[178:181], v171 offset:2048
	ds_read_b128 v[182:185], v171 offset:3072
	ds_read_b128 v[186:189], v163
	ds_read_b128 v[190:193], v163 offset:1024
	ds_read_b128 v[194:197], v162
	ds_read_b128 v[198:201], v162 offset:1024
	ds_read_b128 v[202:205], v161
	ds_read_b128 v[208:211], v161 offset:1024
	ds_read_b128 v[218:221], v160
	ds_read_b128 v[222:225], v160 offset:1024
	v_add_u32_e32 v172, 0xc000, v158
	v_lshl_add_u64 v[214:215], s[92:93], 0, v[148:149]
	v_readfirstlane_b32 s56, v172
	v_lshl_add_u64 v[216:217], v[214:215], 0, s[88:89]
	s_mov_b32 m0, s56
	v_add_u32_e32 v173, 0xe000, v158
	global_load_lds_dwordx4 v[216:217], off
	v_lshl_add_u64 v[216:217], s[92:93], 0, v[150:151]
	v_readfirstlane_b32 s56, v173
	v_lshl_add_u64 v[226:227], v[216:217], 0, s[88:89]
	s_mov_b32 m0, s56
	s_nop 0
	global_load_lds_dwordx4 v[226:227], off
	s_waitcnt lgkmcnt(8)
	s_barrier
	s_waitcnt lgkmcnt(0)
	s_waitcnt lgkmcnt(0)
	v_mfma_f32_16x16x32_bf16 v[0:3], v[136:139], v[186:189], v[0:3]
	v_mfma_f32_16x16x32_bf16 v[4:7], v[178:181], v[186:189], v[4:7]
	v_mfma_f32_16x16x32_bf16 v[8:11], v[136:139], v[194:197], v[8:11]
	v_mfma_f32_16x16x32_bf16 v[16:19], v[178:181], v[194:197], v[16:19]
	v_mfma_f32_16x16x32_bf16 v[28:31], v[136:139], v[202:205], v[28:31]
	v_mfma_f32_16x16x32_bf16 v[40:43], v[178:181], v[202:205], v[40:43]
	v_mfma_f32_16x16x32_bf16 v[52:55], v[136:139], v[218:221], v[52:55]
	v_mfma_f32_16x16x32_bf16 v[64:67], v[178:181], v[218:221], v[64:67]
	v_mfma_f32_16x16x32_bf16 v[0:3], v[174:177], v[190:193], v[0:3]
	v_mfma_f32_16x16x32_bf16 v[4:7], v[182:185], v[190:193], v[4:7]
	v_mfma_f32_16x16x32_bf16 v[8:11], v[174:177], v[198:201], v[8:11]
	v_mfma_f32_16x16x32_bf16 v[16:19], v[182:185], v[198:201], v[16:19]
	v_mfma_f32_16x16x32_bf16 v[28:31], v[174:177], v[208:211], v[28:31]
	v_mfma_f32_16x16x32_bf16 v[40:43], v[182:185], v[208:211], v[40:43]
	v_mfma_f32_16x16x32_bf16 v[52:55], v[174:177], v[222:225], v[52:55]
	v_mfma_f32_16x16x32_bf16 v[64:67], v[182:185], v[222:225], v[64:67]
	s_barrier
	ds_read_b128 v[226:229], v169
	ds_read_b128 v[230:233], v169 offset:1024
	ds_read_b128 v[234:237], v169 offset:2048
	ds_read_b128 v[238:241], v169 offset:3072
	v_lshl_add_u64 v[242:243], s[92:93], 0, v[144:145]
	v_readfirstlane_b32 s56, v157
	v_lshl_add_u64 v[244:245], v[242:243], 0, s[2:3]
	s_mov_b32 m0, s56
	v_add_u32_e32 v134, 0x2000, v157
	global_load_lds_dwordx4 v[244:245], off
	v_lshl_add_u64 v[244:245], s[92:93], 0, v[146:147]
	v_readfirstlane_b32 s56, v134
	v_lshl_add_u64 v[246:247], v[244:245], 0, s[2:3]
	s_mov_b32 m0, s56
	s_nop 0
	global_load_lds_dwordx4 v[246:247], off
	s_barrier
	s_waitcnt lgkmcnt(0)
	s_waitcnt lgkmcnt(0)
	v_mfma_f32_16x16x32_bf16 v[12:15], v[226:229], v[186:189], v[12:15]
	v_mfma_f32_16x16x32_bf16 v[24:27], v[234:237], v[186:189], v[24:27]
	v_mfma_f32_16x16x32_bf16 v[36:39], v[226:229], v[194:197], v[36:39]
	v_mfma_f32_16x16x32_bf16 v[48:51], v[234:237], v[194:197], v[48:51]
	v_mfma_f32_16x16x32_bf16 v[60:63], v[226:229], v[202:205], v[60:63]
	v_mfma_f32_16x16x32_bf16 v[72:75], v[234:237], v[202:205], v[72:75]
	v_mfma_f32_16x16x32_bf16 v[80:83], v[226:229], v[218:221], v[80:83]
	v_mfma_f32_16x16x32_bf16 v[88:91], v[234:237], v[218:221], v[88:91]
	v_mfma_f32_16x16x32_bf16 v[12:15], v[230:233], v[190:193], v[12:15]
	v_mfma_f32_16x16x32_bf16 v[24:27], v[238:241], v[190:193], v[24:27]
	v_mfma_f32_16x16x32_bf16 v[36:39], v[230:233], v[198:201], v[36:39]
	v_mfma_f32_16x16x32_bf16 v[48:51], v[238:241], v[198:201], v[48:51]
	v_mfma_f32_16x16x32_bf16 v[60:63], v[230:233], v[208:211], v[60:63]
	v_mfma_f32_16x16x32_bf16 v[72:75], v[238:241], v[208:211], v[72:75]
	v_mfma_f32_16x16x32_bf16 v[80:83], v[230:233], v[222:225], v[80:83]
	v_mfma_f32_16x16x32_bf16 v[88:91], v[238:241], v[222:225], v[88:91]
	v_readfirstlane_b32 s56, v158
	v_add_u32_e32 v134, 0x2000, v158
	v_lshl_add_u64 v[246:247], v[214:215], 0, s[8:9]
	s_mov_b32 m0, s56
	v_readfirstlane_b32 s56, v134
	s_barrier
	ds_read_b128 v[186:189], v163 offset:16384
	ds_read_b128 v[190:193], v163 offset:17408
	ds_read_b128 v[194:197], v162 offset:16384
	ds_read_b128 v[198:201], v162 offset:17408
	ds_read_b128 v[202:205], v161 offset:16384
	ds_read_b128 v[208:211], v161 offset:17408
	ds_read_b128 v[218:221], v160 offset:16384
	ds_read_b128 v[222:225], v160 offset:17408
	global_load_lds_dwordx4 v[246:247], off
	v_lshl_add_u64 v[246:247], v[216:217], 0, s[8:9]
	s_mov_b32 m0, s56
	s_nop 0
	global_load_lds_dwordx4 v[246:247], off
	s_barrier
	s_waitcnt lgkmcnt(0)
	s_waitcnt lgkmcnt(0)
	v_mfma_f32_16x16x32_bf16 v[20:23], v[136:139], v[186:189], v[20:23]
	v_mfma_f32_16x16x32_bf16 v[32:35], v[178:181], v[186:189], v[32:35]
	v_mfma_f32_16x16x32_bf16 v[44:47], v[136:139], v[194:197], v[44:47]
	v_mfma_f32_16x16x32_bf16 v[56:59], v[178:181], v[194:197], v[56:59]
	v_mfma_f32_16x16x32_bf16 v[68:71], v[136:139], v[202:205], v[68:71]
	v_mfma_f32_16x16x32_bf16 v[76:79], v[178:181], v[202:205], v[76:79]
	v_mfma_f32_16x16x32_bf16 v[84:87], v[136:139], v[218:221], v[84:87]
	v_mfma_f32_16x16x32_bf16 v[92:95], v[178:181], v[218:221], v[92:95]
	v_mfma_f32_16x16x32_bf16 v[20:23], v[174:177], v[190:193], v[20:23]
	v_mfma_f32_16x16x32_bf16 v[32:35], v[182:185], v[190:193], v[32:35]
	v_mfma_f32_16x16x32_bf16 v[44:47], v[174:177], v[198:201], v[44:47]
	v_mfma_f32_16x16x32_bf16 v[56:59], v[182:185], v[198:201], v[56:59]
	v_mfma_f32_16x16x32_bf16 v[68:71], v[174:177], v[208:211], v[68:71]
	v_mfma_f32_16x16x32_bf16 v[76:79], v[182:185], v[208:211], v[76:79]
	v_mfma_f32_16x16x32_bf16 v[84:87], v[174:177], v[222:225], v[84:87]
	v_mfma_f32_16x16x32_bf16 v[92:95], v[182:185], v[222:225], v[92:95]
	s_barrier
; #define STAGE(P, BASE, br, kt) STAGET(tid_, P, BASE, br, kt)
; #define LDA(dst, b, h) UFOR(m, 4) UFOR(k, 2) \
;     dst[m][k] = *reinterpret_cast<const bf16x8*>((char*)SA(b, h) + lds_byte(wr * 64 + m * 16 + fr, k * 32 + fq * 8))
; #define LDB(dst, b, h) UFOR(n, 2) UFOR(k, 2) \
;     dst[n][k] = *reinterpret_cast<const bf16x8*>((char*)SB(b, h) + lds_byte(wc * 32 + n * 16 + fr, k * 32 + fq * 8))
; #define MMA(ai, bj, At, Bq) do { __builtin_amdgcn_s_setprio(1); \
;     UFOR(m, 4) UFOR(n, 2) UFOR(k, 2) \
;       acc[ai][bj][m][n] = __builtin_amdgcn_mfma_f32_16x16x32_bf16(Bq[n][k], At[m][k], acc[ai][bj][m][n], 0, 0, 0); \
;     __builtin_amdgcn_s_setprio(0); } while (0)
; #define WAIT_V(n) asm volatile("s_waitcnt vmcnt(" #n ")" ::: "memory")
; #define WAIT_L(n) asm volatile("s_waitcnt lgkmcnt(" #n ")" ::: "memory")
; #define BAR __builtin_amdgcn_s_barrier()
; #define SCHED __builtin_amdgcn_sched_barrier(0)
; template <int EPI, int K, int KL> ...
;     ...
;     STAGE(SB(0, 1), Bt, bcol + HALF, t + 2);
;     WAIT_V(6); BAR; MMA(1, 1, At, B1); BAR;
;     LDB(B0, 1, 0); SCHED; LDA(At, 1, 0); STAGE(SA(0, 1), A, brow + HALF, t + 2);
;     WAIT_L(8); BAR; WAIT_L(0); MMA(0, 0, At, B0); BAR; SCHED;
;     LDB(B1, 1, 1); STAGE(SB(1, 0), Bt, bcol, t + 3);
;     BAR; WAIT_L(0); MMA(0, 1, At, B1); BAR;
;     LDA(At, 1, 1); STAGE(SA(1, 0), A, brow, t + 3);
;     BAR; WAIT_L(0); MMA(1, 0, At, B0); BAR; SCHED;
;     STAGE(SB(1, 1), Bt, bcol + HALF, t + 3);
	v_readfirstlane_b32 s56, v159
	v_add_u32_e32 v134, 0x2000, v159
	v_lshl_add_u64 v[136:137], v[242:243], 0, s[96:97]
	s_mov_b32 m0, s56
	v_readfirstlane_b32 s56, v134
	global_load_lds_dwordx4 v[136:137], off
	v_lshl_add_u64 v[136:137], v[244:245], 0, s[96:97]
	s_mov_b32 m0, s56
	s_nop 0
	global_load_lds_dwordx4 v[136:137], off
	s_waitcnt vmcnt(6)
	s_barrier
	v_mfma_f32_16x16x32_bf16 v[96:99], v[226:229], v[186:189], v[96:99]
	v_mfma_f32_16x16x32_bf16 v[100:103], v[234:237], v[186:189], v[100:103]
	v_mfma_f32_16x16x32_bf16 v[104:107], v[226:229], v[194:197], v[104:107]
	v_mfma_f32_16x16x32_bf16 v[108:111], v[234:237], v[194:197], v[108:111]
	v_mfma_f32_16x16x32_bf16 v[112:115], v[226:229], v[202:205], v[112:115]
	v_mfma_f32_16x16x32_bf16 v[116:119], v[234:237], v[202:205], v[116:119]
	v_mfma_f32_16x16x32_bf16 v[120:123], v[226:229], v[218:221], v[120:123]
	v_mfma_f32_16x16x32_bf16 v[124:127], v[234:237], v[218:221], v[124:127]
	v_mfma_f32_16x16x32_bf16 v[96:99], v[230:233], v[190:193], v[96:99]
	v_mfma_f32_16x16x32_bf16 v[100:103], v[238:241], v[190:193], v[100:103]
	v_mfma_f32_16x16x32_bf16 v[104:107], v[230:233], v[198:201], v[104:107]
	v_mfma_f32_16x16x32_bf16 v[108:111], v[238:241], v[198:201], v[108:111]
	v_mfma_f32_16x16x32_bf16 v[112:115], v[230:233], v[208:211], v[112:115]
	v_mfma_f32_16x16x32_bf16 v[116:119], v[238:241], v[208:211], v[116:119]
	v_mfma_f32_16x16x32_bf16 v[120:123], v[230:233], v[222:225], v[120:123]
	v_mfma_f32_16x16x32_bf16 v[124:127], v[238:241], v[222:225], v[124:127]
	s_barrier
	ds_read_b128 v[136:139], v166
	ds_read_b128 v[174:177], v166 offset:1024
	ds_read_b128 v[178:181], v166 offset:2048
	ds_read_b128 v[182:185], v166 offset:3072
	ds_read_b128 v[186:189], v163 offset:32768
	ds_read_b128 v[190:193], v163 offset:33792
	ds_read_b128 v[194:197], v162 offset:32768
	ds_read_b128 v[198:201], v162 offset:33792
	ds_read_b128 v[202:205], v161 offset:32768
	ds_read_b128 v[208:211], v161 offset:33792
	ds_read_b128 v[218:221], v160 offset:32768
	ds_read_b128 v[222:225], v160 offset:33792
	v_add_u32_e32 v134, 0x4000, v158
	v_lshl_add_u64 v[226:227], v[214:215], 0, s[12:13]
	v_readfirstlane_b32 s56, v134
	v_add_u32_e32 v134, 0x6000, v158
	s_mov_b32 m0, s56
	v_readfirstlane_b32 s56, v134
	global_load_lds_dwordx4 v[226:227], off
	v_lshl_add_u64 v[226:227], v[216:217], 0, s[12:13]
	s_mov_b32 m0, s56
	s_nop 0
	global_load_lds_dwordx4 v[226:227], off
	s_waitcnt lgkmcnt(8)
	s_barrier
	s_waitcnt lgkmcnt(0)
	s_waitcnt lgkmcnt(0)
	v_mfma_f32_16x16x32_bf16 v[0:3], v[136:139], v[186:189], v[0:3]
	v_mfma_f32_16x16x32_bf16 v[4:7], v[178:181], v[186:189], v[4:7]
	v_mfma_f32_16x16x32_bf16 v[8:11], v[136:139], v[194:197], v[8:11]
	v_mfma_f32_16x16x32_bf16 v[16:19], v[178:181], v[194:197], v[16:19]
	v_mfma_f32_16x16x32_bf16 v[28:31], v[136:139], v[202:205], v[28:31]
	v_mfma_f32_16x16x32_bf16 v[40:43], v[178:181], v[202:205], v[40:43]
	v_mfma_f32_16x16x32_bf16 v[52:55], v[136:139], v[218:221], v[52:55]
	v_mfma_f32_16x16x32_bf16 v[64:67], v[178:181], v[218:221], v[64:67]
	v_mfma_f32_16x16x32_bf16 v[0:3], v[174:177], v[190:193], v[0:3]
	v_mfma_f32_16x16x32_bf16 v[4:7], v[182:185], v[190:193], v[4:7]
	v_mfma_f32_16x16x32_bf16 v[8:11], v[174:177], v[198:201], v[8:11]
	v_mfma_f32_16x16x32_bf16 v[16:19], v[182:185], v[198:201], v[16:19]
	v_mfma_f32_16x16x32_bf16 v[28:31], v[174:177], v[208:211], v[28:31]
	v_mfma_f32_16x16x32_bf16 v[40:43], v[182:185], v[208:211], v[40:43]
	v_mfma_f32_16x16x32_bf16 v[52:55], v[174:177], v[222:225], v[52:55]
	v_mfma_f32_16x16x32_bf16 v[64:67], v[182:185], v[222:225], v[64:67]
	s_barrier
	ds_read_b128 v[226:229], v164
	ds_read_b128 v[230:233], v164 offset:1024
	ds_read_b128 v[234:237], v164 offset:2048
	ds_read_b128 v[238:241], v164 offset:3072
	v_readfirstlane_b32 s56, v165
	v_add_u32_e32 v134, 0x2000, v165
	v_lshl_add_u64 v[246:247], v[242:243], 0, s[80:81]
	s_mov_b32 m0, s56
	v_readfirstlane_b32 s56, v134
	global_load_lds_dwordx4 v[246:247], off
	v_lshl_add_u64 v[246:247], v[244:245], 0, s[80:81]
	s_mov_b32 m0, s56
	s_nop 0
	global_load_lds_dwordx4 v[246:247], off
	s_barrier
	s_waitcnt lgkmcnt(0)
	s_waitcnt lgkmcnt(0)
	v_mfma_f32_16x16x32_bf16 v[12:15], v[226:229], v[186:189], v[12:15]
	v_mfma_f32_16x16x32_bf16 v[24:27], v[234:237], v[186:189], v[24:27]
	v_mfma_f32_16x16x32_bf16 v[36:39], v[226:229], v[194:197], v[36:39]
	v_mfma_f32_16x16x32_bf16 v[48:51], v[234:237], v[194:197], v[48:51]
	v_mfma_f32_16x16x32_bf16 v[60:63], v[226:229], v[202:205], v[60:63]
	v_mfma_f32_16x16x32_bf16 v[72:75], v[234:237], v[202:205], v[72:75]
	v_mfma_f32_16x16x32_bf16 v[80:83], v[226:229], v[218:221], v[80:83]
	v_mfma_f32_16x16x32_bf16 v[88:91], v[234:237], v[218:221], v[88:91]
	v_mfma_f32_16x16x32_bf16 v[12:15], v[230:233], v[190:193], v[12:15]
	v_mfma_f32_16x16x32_bf16 v[24:27], v[238:241], v[190:193], v[24:27]
	v_mfma_f32_16x16x32_bf16 v[36:39], v[230:233], v[198:201], v[36:39]
	v_mfma_f32_16x16x32_bf16 v[48:51], v[238:241], v[198:201], v[48:51]
	v_mfma_f32_16x16x32_bf16 v[60:63], v[230:233], v[208:211], v[60:63]
	v_mfma_f32_16x16x32_bf16 v[72:75], v[238:241], v[208:211], v[72:75]
	v_mfma_f32_16x16x32_bf16 v[80:83], v[230:233], v[222:225], v[80:83]
	v_mfma_f32_16x16x32_bf16 v[88:91], v[238:241], v[222:225], v[88:91]
	v_readfirstlane_b32 s56, v167
	v_lshl_add_u64 v[214:215], v[214:215], 0, s[16:17]
	s_mov_b32 m0, s56
	v_readfirstlane_b32 s56, v168
	s_barrier
	ds_read_b128 v[186:189], v163 offset:49152
	ds_read_b128 v[190:193], v163 offset:50176
	ds_read_b128 v[194:197], v162 offset:49152
	ds_read_b128 v[198:201], v162 offset:50176
	ds_read_b128 v[202:205], v161 offset:49152
	ds_read_b128 v[208:211], v161 offset:50176
	ds_read_b128 v[218:221], v160 offset:49152
	ds_read_b128 v[222:225], v160 offset:50176
	global_load_lds_dwordx4 v[214:215], off
	v_lshl_add_u64 v[214:215], v[216:217], 0, s[16:17]
	s_mov_b32 m0, s56
	s_nop 0
	global_load_lds_dwordx4 v[214:215], off
	s_barrier
; #define STAGE(P, BASE, br, kt) STAGET(tid_, P, BASE, br, kt)
; #define LDA(dst, b, h) UFOR(m, 4) UFOR(k, 2) \
;     dst[m][k] = *reinterpret_cast<const bf16x8*>((char*)SA(b, h) + lds_byte(wr * 64 + m * 16 + fr, k * 32 + fq * 8))
; #define LDB(dst, b, h) UFOR(n, 2) UFOR(k, 2) \
;     dst[n][k] = *reinterpret_cast<const bf16x8*>((char*)SB(b, h) + lds_byte(wc * 32 + n * 16 + fr, k * 32 + fq * 8))
; #define MMA(ai, bj, At, Bq) do { __builtin_amdgcn_s_setprio(1); \
;     UFOR(m, 4) UFOR(n, 2) UFOR(k, 2) \
;       acc[ai][bj][m][n] = __builtin_amdgcn_mfma_f32_16x16x32_bf16(Bq[n][k], At[m][k], acc[ai][bj][m][n], 0, 0, 0); \
;     __builtin_amdgcn_s_setprio(0); } while (0)
; #define WAIT_V(n) asm volatile("s_waitcnt vmcnt(" #n ")" ::: "memory")
; #define WAIT_L(n) asm volatile("s_waitcnt lgkmcnt(" #n ")" ::: "memory")
; #define BAR __builtin_amdgcn_s_barrier()
; template <int EPI, int K, int KL> ...
;     ...
;     STAGE(SB(1, 1), Bt, bcol + HALF, t + 3);
;     WAIT_V(6); BAR; MMA(1, 1, At, B1); BAR;
;   }
;   { LDB(B0, 0, 0); LDA(At, 0, 0); STAGE(SA(1, 1), A, brow + HALF, nt - 1);
;     BAR; WAIT_L(0); MMA(0, 0, At, B0); BAR;
;     LDB(B1, 0, 1); BAR; WAIT_L(0); MMA(0, 1, At, B1); BAR;
;     LDA(At, 0, 1); WAIT_V(4); BAR; WAIT_L(0); MMA(1, 0, At, B0); MMA(1, 1, At, B1); BAR; }
	s_waitcnt lgkmcnt(0)
	s_waitcnt lgkmcnt(0)
	v_mfma_f32_16x16x32_bf16 v[20:23], v[136:139], v[186:189], v[20:23]
	v_mfma_f32_16x16x32_bf16 v[32:35], v[178:181], v[186:189], v[32:35]
	v_mfma_f32_16x16x32_bf16 v[44:47], v[136:139], v[194:197], v[44:47]
	v_mfma_f32_16x16x32_bf16 v[56:59], v[178:181], v[194:197], v[56:59]
	v_mfma_f32_16x16x32_bf16 v[68:71], v[136:139], v[202:205], v[68:71]
	v_mfma_f32_16x16x32_bf16 v[76:79], v[178:181], v[202:205], v[76:79]
	v_mfma_f32_16x16x32_bf16 v[84:87], v[136:139], v[218:221], v[84:87]
	v_mfma_f32_16x16x32_bf16 v[92:95], v[178:181], v[218:221], v[92:95]
	v_mfma_f32_16x16x32_bf16 v[20:23], v[174:177], v[190:193], v[20:23]
	v_mfma_f32_16x16x32_bf16 v[32:35], v[182:185], v[190:193], v[32:35]
	v_mfma_f32_16x16x32_bf16 v[44:47], v[174:177], v[198:201], v[44:47]
	v_mfma_f32_16x16x32_bf16 v[56:59], v[182:185], v[198:201], v[56:59]
	v_mfma_f32_16x16x32_bf16 v[68:71], v[174:177], v[208:211], v[68:71]
	v_mfma_f32_16x16x32_bf16 v[76:79], v[182:185], v[208:211], v[76:79]
	v_mfma_f32_16x16x32_bf16 v[84:87], v[174:177], v[222:225], v[84:87]
	v_mfma_f32_16x16x32_bf16 v[92:95], v[182:185], v[222:225], v[92:95]
	s_barrier
	v_readfirstlane_b32 s56, v170
	v_add_u32_e32 v134, 0x2000, v170
	v_lshl_add_u64 v[136:137], v[242:243], 0, s[90:91]
	s_mov_b32 m0, s56
	v_readfirstlane_b32 s56, v134
	global_load_lds_dwordx4 v[136:137], off
	v_lshl_add_u64 v[136:137], v[244:245], 0, s[90:91]
	s_mov_b32 m0, s56
	s_nop 0
	global_load_lds_dwordx4 v[136:137], off
	s_waitcnt vmcnt(6)
	s_barrier
	v_mfma_f32_16x16x32_bf16 v[96:99], v[226:229], v[186:189], v[96:99]
	v_mfma_f32_16x16x32_bf16 v[100:103], v[234:237], v[186:189], v[100:103]
	v_mfma_f32_16x16x32_bf16 v[104:107], v[226:229], v[194:197], v[104:107]
	v_mfma_f32_16x16x32_bf16 v[108:111], v[234:237], v[194:197], v[108:111]
	v_mfma_f32_16x16x32_bf16 v[112:115], v[226:229], v[202:205], v[112:115]
	v_mfma_f32_16x16x32_bf16 v[116:119], v[234:237], v[202:205], v[116:119]
	v_mfma_f32_16x16x32_bf16 v[120:123], v[226:229], v[218:221], v[120:123]
	v_mfma_f32_16x16x32_bf16 v[124:127], v[234:237], v[218:221], v[124:127]
	v_mfma_f32_16x16x32_bf16 v[96:99], v[230:233], v[190:193], v[96:99]
	v_mfma_f32_16x16x32_bf16 v[100:103], v[238:241], v[190:193], v[100:103]
	v_mfma_f32_16x16x32_bf16 v[104:107], v[230:233], v[198:201], v[104:107]
	v_mfma_f32_16x16x32_bf16 v[108:111], v[238:241], v[198:201], v[108:111]
	v_mfma_f32_16x16x32_bf16 v[112:115], v[230:233], v[208:211], v[112:115]
	v_mfma_f32_16x16x32_bf16 v[116:119], v[238:241], v[208:211], v[116:119]
	v_mfma_f32_16x16x32_bf16 v[120:123], v[230:233], v[222:225], v[120:123]
	v_mfma_f32_16x16x32_bf16 v[124:127], v[238:241], v[222:225], v[124:127]
	s_add_i32 s53, s53, 2
	v_lshl_add_u64 v[144:145], v[144:145], 0, s[20:21]
	v_lshl_add_u64 v[146:147], v[146:147], 0, s[20:21]
	v_lshl_add_u64 v[148:149], v[148:149], 0, s[20:21]
	s_cmp_lt_u32 s53, 28
	v_lshl_add_u64 v[150:151], v[150:151], 0, s[20:21]
	s_cbranch_scc1 .Lkrot_1107
	s_barrier
	s_add_u32 s40, s40, 0x80f80
	s_addc_u32 s41, s41, 0
	v_lshl_add_u64 v[130:131], s[40:41], 0, v[130:131]
	v_readfirstlane_b32 s53, v172
	v_lshl_add_u64 v[128:129], v[128:129], 1, v[130:131]
	s_mov_b32 m0, s53
	ds_read_b128 v[136:139], v171
	ds_read_b128 v[144:147], v171 offset:1024
	ds_read_b128 v[148:151], v171 offset:2048
	ds_read_b128 v[174:177], v171 offset:3072
	ds_read_b128 v[178:181], v163
	ds_read_b128 v[182:185], v163 offset:1024
	ds_read_b128 v[186:189], v162
	ds_read_b128 v[190:193], v162 offset:1024
	ds_read_b128 v[194:197], v161
	ds_read_b128 v[198:201], v161 offset:1024
	ds_read_b128 v[202:205], v160
	ds_read_b128 v[208:211], v160 offset:1024
	global_load_lds_dwordx4 v[128:129], off
	v_lshl_add_u64 v[128:129], s[40:41], 0, v[142:143]
	v_readfirstlane_b32 s40, v173
	v_lshl_add_u64 v[128:129], v[140:141], 1, v[128:129]
	s_mov_b32 m0, s40
	s_nop 0
	global_load_lds_dwordx4 v[128:129], off
	s_barrier
	s_waitcnt lgkmcnt(0)
	s_waitcnt lgkmcnt(0)
	v_mfma_f32_16x16x32_bf16 v[0:3], v[136:139], v[178:181], v[0:3]
	v_mfma_f32_16x16x32_bf16 v[4:7], v[148:151], v[178:181], v[4:7]
	v_mfma_f32_16x16x32_bf16 v[8:11], v[136:139], v[186:189], v[8:11]
	v_mfma_f32_16x16x32_bf16 v[16:19], v[148:151], v[186:189], v[16:19]
	v_mfma_f32_16x16x32_bf16 v[28:31], v[136:139], v[194:197], v[28:31]
	v_mfma_f32_16x16x32_bf16 v[40:43], v[148:151], v[194:197], v[40:43]
	v_mfma_f32_16x16x32_bf16 v[52:55], v[136:139], v[202:205], v[52:55]
	v_mfma_f32_16x16x32_bf16 v[64:67], v[148:151], v[202:205], v[64:67]
	v_mfma_f32_16x16x32_bf16 v[0:3], v[144:147], v[182:185], v[0:3]
	v_mfma_f32_16x16x32_bf16 v[4:7], v[174:177], v[182:185], v[4:7]
	v_mfma_f32_16x16x32_bf16 v[8:11], v[144:147], v[190:193], v[8:11]
	v_mfma_f32_16x16x32_bf16 v[16:19], v[174:177], v[190:193], v[16:19]
	v_mfma_f32_16x16x32_bf16 v[28:31], v[144:147], v[198:201], v[28:31]
	v_mfma_f32_16x16x32_bf16 v[40:43], v[174:177], v[198:201], v[40:43]
	v_mfma_f32_16x16x32_bf16 v[52:55], v[144:147], v[208:211], v[52:55]
	v_mfma_f32_16x16x32_bf16 v[64:67], v[174:177], v[208:211], v[64:67]
	s_barrier
	ds_read_b128 v[128:131], v169
	ds_read_b128 v[140:143], v169 offset:1024
	ds_read_b128 v[170:173], v169 offset:2048
	ds_read_b128 v[218:221], v169 offset:3072
	s_barrier
; #define LDA(dst, b, h) UFOR(m, 4) UFOR(k, 2) \
;     dst[m][k] = *reinterpret_cast<const bf16x8*>((char*)SA(b, h) + lds_byte(wr * 64 + m * 16 + fr, k * 32 + fq * 8))
; #define LDB(dst, b, h) UFOR(n, 2) UFOR(k, 2) \
;     dst[n][k] = *reinterpret_cast<const bf16x8*>((char*)SB(b, h) + lds_byte(wc * 32 + n * 16 + fr, k * 32 + fq * 8))
; #define MMA(ai, bj, At, Bq) do { __builtin_amdgcn_s_setprio(1); \
;     UFOR(m, 4) UFOR(n, 2) UFOR(k, 2) \
;       acc[ai][bj][m][n] = __builtin_amdgcn_mfma_f32_16x16x32_bf16(Bq[n][k], At[m][k], acc[ai][bj][m][n], 0, 0, 0); \
;     __builtin_amdgcn_s_setprio(0); } while (0)
; #define WAIT_V(n) asm volatile("s_waitcnt vmcnt(" #n ")" ::: "memory")
; #define WAIT_L(n) asm volatile("s_waitcnt lgkmcnt(" #n ")" ::: "memory")
; #define BAR __builtin_amdgcn_s_barrier()
; template <int EPI, int K, int KL> ...
;     ...
;     BAR; WAIT_L(0); MMA(0, 0, At, B0); BAR;
;     LDB(B1, 0, 1); BAR; WAIT_L(0); MMA(0, 1, At, B1); BAR;
;     LDA(At, 0, 1); WAIT_V(4); BAR; WAIT_L(0); MMA(1, 0, At, B0); MMA(1, 1, At, B1); BAR; }
;   { LDB(B0, 1, 0); LDA(At, 1, 0); WAIT_V(2); BAR; WAIT_L(0); MMA(0, 0, At, B0); BAR;
;     LDB(B1, 1, 1); WAIT_V(0); BAR; WAIT_L(0); MMA(0, 1, At, B1); BAR;
	s_waitcnt lgkmcnt(0)
	s_waitcnt lgkmcnt(0)
	v_mfma_f32_16x16x32_bf16 v[12:15], v[128:131], v[178:181], v[12:15]
	v_mfma_f32_16x16x32_bf16 v[24:27], v[170:173], v[178:181], v[24:27]
	v_mfma_f32_16x16x32_bf16 v[36:39], v[128:131], v[186:189], v[36:39]
	v_mfma_f32_16x16x32_bf16 v[48:51], v[170:173], v[186:189], v[48:51]
	v_mfma_f32_16x16x32_bf16 v[60:63], v[128:131], v[194:197], v[60:63]
	v_mfma_f32_16x16x32_bf16 v[72:75], v[170:173], v[194:197], v[72:75]
	v_mfma_f32_16x16x32_bf16 v[80:83], v[128:131], v[202:205], v[80:83]
	v_mfma_f32_16x16x32_bf16 v[12:15], v[140:143], v[182:185], v[12:15]
	v_mfma_f32_16x16x32_bf16 v[24:27], v[218:221], v[182:185], v[24:27]
	v_mfma_f32_16x16x32_bf16 v[36:39], v[140:143], v[190:193], v[36:39]
	v_mfma_f32_16x16x32_bf16 v[48:51], v[218:221], v[190:193], v[48:51]
	v_mfma_f32_16x16x32_bf16 v[60:63], v[140:143], v[198:201], v[60:63]
	v_mfma_f32_16x16x32_bf16 v[72:75], v[218:221], v[198:201], v[72:75]
	v_mfma_f32_16x16x32_bf16 v[178:181], v[140:143], v[208:211], v[80:83]
	v_mfma_f32_16x16x32_bf16 v[80:83], v[170:173], v[202:205], v[88:91]
	v_mfma_f32_16x16x32_bf16 v[182:185], v[218:221], v[208:211], v[80:83]
	s_barrier
	s_nop 5
	ds_read_b128 v[80:83], v163 offset:16384
	ds_read_b128 v[88:91], v163 offset:17408
	ds_read_b128 v[186:189], v162 offset:16384
	ds_read_b128 v[190:193], v162 offset:17408
	ds_read_b128 v[194:197], v161 offset:16384
	ds_read_b128 v[198:201], v161 offset:17408
	ds_read_b128 v[202:205], v160 offset:16384
	ds_read_b128 v[208:211], v160 offset:17408
	s_waitcnt vmcnt(4)
	s_barrier
	s_waitcnt lgkmcnt(0)
	s_waitcnt lgkmcnt(0)
	v_mfma_f32_16x16x32_bf16 v[56:59], v[148:151], v[186:189], v[56:59]
	v_mfma_f32_16x16x32_bf16 v[222:225], v[174:177], v[190:193], v[56:59]
	v_mfma_f32_16x16x32_bf16 v[56:59], v[136:139], v[194:197], v[68:71]
	v_mfma_f32_16x16x32_bf16 v[226:229], v[144:147], v[198:201], v[56:59]
	v_mfma_f32_16x16x32_bf16 v[56:59], v[148:151], v[194:197], v[76:79]
	v_mfma_f32_16x16x32_bf16 v[20:23], v[136:139], v[80:83], v[20:23]
	v_mfma_f32_16x16x32_bf16 v[32:35], v[148:151], v[80:83], v[32:35]
	v_mfma_f32_16x16x32_bf16 v[44:47], v[136:139], v[186:189], v[44:47]
	v_mfma_f32_16x16x32_bf16 v[230:233], v[174:177], v[198:201], v[56:59]
	v_mfma_f32_16x16x32_bf16 v[56:59], v[136:139], v[202:205], v[84:87]
	v_mfma_f32_16x16x32_bf16 v[20:23], v[144:147], v[88:91], v[20:23]
	v_mfma_f32_16x16x32_bf16 v[32:35], v[174:177], v[88:91], v[32:35]
	v_mfma_f32_16x16x32_bf16 v[44:47], v[144:147], v[190:193], v[44:47]
	v_mfma_f32_16x16x32_bf16 v[136:139], v[144:147], v[208:211], v[56:59]
	v_mfma_f32_16x16x32_bf16 v[56:59], v[148:151], v[202:205], v[92:95]
	v_mfma_f32_16x16x32_bf16 v[144:147], v[174:177], v[208:211], v[56:59]
	v_mfma_f32_16x16x32_bf16 v[56:59], v[128:131], v[80:83], v[96:99]
	v_mfma_f32_16x16x32_bf16 v[148:151], v[140:143], v[88:91], v[56:59]
	v_mfma_f32_16x16x32_bf16 v[56:59], v[170:173], v[80:83], v[100:103]
	v_mfma_f32_16x16x32_bf16 v[174:177], v[218:221], v[88:91], v[56:59]
	v_mfma_f32_16x16x32_bf16 v[56:59], v[128:131], v[186:189], v[104:107]
	v_mfma_f32_16x16x32_bf16 v[234:237], v[140:143], v[190:193], v[56:59]
	v_mfma_f32_16x16x32_bf16 v[56:59], v[170:173], v[186:189], v[108:111]
	v_mfma_f32_16x16x32_bf16 v[186:189], v[218:221], v[190:193], v[56:59]
	v_mfma_f32_16x16x32_bf16 v[56:59], v[128:131], v[194:197], v[112:115]
	v_mfma_f32_16x16x32_bf16 v[190:193], v[140:143], v[198:201], v[56:59]
	v_mfma_f32_16x16x32_bf16 v[56:59], v[170:173], v[194:197], v[116:119]
	v_mfma_f32_16x16x32_bf16 v[194:197], v[218:221], v[198:201], v[56:59]
	v_mfma_f32_16x16x32_bf16 v[56:59], v[128:131], v[202:205], v[120:123]
	v_mfma_f32_16x16x32_bf16 v[128:131], v[140:143], v[208:211], v[56:59]
	v_mfma_f32_16x16x32_bf16 v[56:59], v[170:173], v[202:205], v[124:127]
	v_mfma_f32_16x16x32_bf16 v[140:143], v[218:221], v[208:211], v[56:59]
	s_barrier
	ds_read_b128 v[168:171], v166
	ds_read_b128 v[198:201], v166 offset:1024
	ds_read_b128 v[202:205], v166 offset:2048
	ds_read_b128 v[208:211], v166 offset:3072
	s_nop 1
	ds_read_b128 v[56:59], v163 offset:32768
	ds_read_b128 v[68:71], v163 offset:33792
	ds_read_b128 v[76:79], v162 offset:32768
	ds_read_b128 v[80:83], v162 offset:33792
	ds_read_b128 v[218:221], v161 offset:32768
	ds_read_b128 v[238:241], v161 offset:33792
	ds_read_b128 v[242:245], v160 offset:32768
	ds_read_b128 v[246:249], v160 offset:33792
	s_waitcnt vmcnt(2)
	s_barrier
	s_waitcnt lgkmcnt(0)
	s_waitcnt lgkmcnt(0)
	v_mfma_f32_16x16x32_bf16 v[0:3], v[168:171], v[56:59], v[0:3]
	v_mfma_f32_16x16x32_bf16 v[124:127], v[198:201], v[68:71], v[0:3]
	v_mfma_f32_16x16x32_bf16 v[0:3], v[202:205], v[56:59], v[4:7]
	v_mfma_f32_16x16x32_bf16 v[120:123], v[208:211], v[68:71], v[0:3]
	v_mfma_f32_16x16x32_bf16 v[0:3], v[168:171], v[76:79], v[8:11]
	v_mfma_f32_16x16x32_bf16 v[116:119], v[198:201], v[80:83], v[0:3]
	v_mfma_f32_16x16x32_bf16 v[0:3], v[202:205], v[76:79], v[16:19]
	v_mfma_f32_16x16x32_bf16 v[112:115], v[208:211], v[80:83], v[0:3]
	v_mfma_f32_16x16x32_bf16 v[0:3], v[168:171], v[218:221], v[28:31]
	v_mfma_f32_16x16x32_bf16 v[108:111], v[198:201], v[238:241], v[0:3]
	v_mfma_f32_16x16x32_bf16 v[0:3], v[202:205], v[218:221], v[40:43]
	v_mfma_f32_16x16x32_bf16 v[104:107], v[208:211], v[238:241], v[0:3]
	v_mfma_f32_16x16x32_bf16 v[0:3], v[168:171], v[242:245], v[52:55]
	v_mfma_f32_16x16x32_bf16 v[100:103], v[198:201], v[246:249], v[0:3]
	v_mfma_f32_16x16x32_bf16 v[0:3], v[202:205], v[242:245], v[64:67]
	v_mfma_f32_16x16x32_bf16 v[96:99], v[208:211], v[246:249], v[0:3]
	s_barrier
	s_nop 5
	ds_read_b128 v[0:3], v164
	ds_read_b128 v[4:7], v164 offset:1024
	ds_read_b128 v[214:217], v164 offset:2048
	ds_read_b128 v[164:167], v164 offset:3072
	s_waitcnt vmcnt(0)
	s_barrier
; #define UFOR(v, n) _Pragma("unroll") for (int v = 0; v < (n); ++v)
; #define LDA(dst, b, h) UFOR(m, 4) UFOR(k, 2) \
;     dst[m][k] = *reinterpret_cast<const bf16x8*>((char*)SA(b, h) + lds_byte(wr * 64 + m * 16 + fr, k * 32 + fq * 8))
; #define LDB(dst, b, h) UFOR(n, 2) UFOR(k, 2) \
;     dst[n][k] = *reinterpret_cast<const bf16x8*>((char*)SB(b, h) + lds_byte(wc * 32 + n * 16 + fr, k * 32 + fq * 8))
; #define MMA(ai, bj, At, Bq) do { __builtin_amdgcn_s_setprio(1); \
;     UFOR(m, 4) UFOR(n, 2) UFOR(k, 2) \
;       acc[ai][bj][m][n] = __builtin_amdgcn_mfma_f32_16x16x32_bf16(Bq[n][k], At[m][k], acc[ai][bj][m][n], 0, 0, 0); \
;     __builtin_amdgcn_s_setprio(0); } while (0)
; #define WAIT_V(n) asm volatile("s_waitcnt vmcnt(" #n ")" ::: "memory")
; #define WAIT_L(n) asm volatile("s_waitcnt lgkmcnt(" #n ")" ::: "memory")
; #define BAR __builtin_amdgcn_s_barrier()
; template <int EPI, int K, int KL> ...
;     ...
;     LDB(B1, 1, 1); WAIT_V(0); BAR; WAIT_L(0); MMA(0, 1, At, B1); BAR;
;     LDA(At, 1, 1); BAR; WAIT_L(0); MMA(1, 0, At, B0); MMA(1, 1, At, B1); BAR; }
;   if (wr == 0) BAR;
;     ...
;       const int gc = pn * 128 + c4;
;       float wg[4][3], wv[4][3];
;       UFOR(q, 4) UFOR(x, 3) { wg[q][x] = e.cw[(size_t)(gc + q) * 3 + x]; wv[q][x] = e.cw[(size_t)(DFF + gc + q) * 3 + x]; }
	s_waitcnt lgkmcnt(0)
	s_waitcnt lgkmcnt(0)
	v_mfma_f32_16x16x32_bf16 v[8:11], v[0:3], v[56:59], v[12:15]
	v_mfma_f32_16x16x32_bf16 v[92:95], v[4:7], v[68:71], v[8:11]
	v_mfma_f32_16x16x32_bf16 v[8:11], v[214:217], v[56:59], v[24:27]
	v_mfma_f32_16x16x32_bf16 v[88:91], v[164:167], v[68:71], v[8:11]
	v_mfma_f32_16x16x32_bf16 v[8:11], v[0:3], v[76:79], v[36:39]
	v_mfma_f32_16x16x32_bf16 v[84:87], v[4:7], v[80:83], v[8:11]
	v_mfma_f32_16x16x32_bf16 v[8:11], v[214:217], v[76:79], v[48:51]
	v_mfma_f32_16x16x32_bf16 v[80:83], v[164:167], v[80:83], v[8:11]
	v_mfma_f32_16x16x32_bf16 v[8:11], v[0:3], v[218:221], v[60:63]
	v_mfma_f32_16x16x32_bf16 v[76:79], v[4:7], v[238:241], v[8:11]
	v_mfma_f32_16x16x32_bf16 v[8:11], v[214:217], v[218:221], v[72:75]
	v_mfma_f32_16x16x32_bf16 v[72:75], v[164:167], v[238:241], v[8:11]
	v_mfma_f32_16x16x32_bf16 v[8:11], v[0:3], v[242:245], v[178:181]
	v_mfma_f32_16x16x32_bf16 v[68:71], v[4:7], v[246:249], v[8:11]
	v_mfma_f32_16x16x32_bf16 v[8:11], v[214:217], v[242:245], v[182:185]
	v_mfma_f32_16x16x32_bf16 v[64:67], v[164:167], v[246:249], v[8:11]
	s_barrier
	s_nop 5
	ds_read_b128 v[8:11], v163 offset:49152
	ds_read_b128 v[12:15], v163 offset:50176
	ds_read_b128 v[16:19], v162 offset:49152
	ds_read_b128 v[178:181], v162 offset:50176
	ds_read_b128 v[182:185], v161 offset:49152
	ds_read_b128 v[218:221], v161 offset:50176
	ds_read_b128 v[238:241], v160 offset:49152
	ds_read_b128 v[158:161], v160 offset:50176
	s_barrier
	s_waitcnt lgkmcnt(0)
	s_waitcnt lgkmcnt(0)
	v_mfma_f32_16x16x32_bf16 v[20:23], v[168:171], v[8:11], v[20:23]
	v_mfma_f32_16x16x32_bf16 v[60:63], v[198:201], v[12:15], v[20:23]
	v_mfma_f32_16x16x32_bf16 v[20:23], v[202:205], v[8:11], v[32:35]
	v_mfma_f32_16x16x32_bf16 v[56:59], v[208:211], v[12:15], v[20:23]
	v_mfma_f32_16x16x32_bf16 v[20:23], v[168:171], v[16:19], v[44:47]
	v_mfma_f32_16x16x32_bf16 v[52:55], v[198:201], v[178:181], v[20:23]
	v_mfma_f32_16x16x32_bf16 v[20:23], v[202:205], v[16:19], v[222:225]
	v_mfma_f32_16x16x32_bf16 v[48:51], v[208:211], v[178:181], v[20:23]
	v_mfma_f32_16x16x32_bf16 v[20:23], v[168:171], v[182:185], v[226:229]
	v_mfma_f32_16x16x32_bf16 v[44:47], v[198:201], v[218:221], v[20:23]
	v_mfma_f32_16x16x32_bf16 v[20:23], v[202:205], v[182:185], v[230:233]
	v_mfma_f32_16x16x32_bf16 v[40:43], v[208:211], v[218:221], v[20:23]
	v_mfma_f32_16x16x32_bf16 v[20:23], v[168:171], v[238:241], v[136:139]
	v_mfma_f32_16x16x32_bf16 v[36:39], v[198:201], v[158:161], v[20:23]
	v_mfma_f32_16x16x32_bf16 v[20:23], v[202:205], v[238:241], v[144:147]
	v_mfma_f32_16x16x32_bf16 v[32:35], v[208:211], v[158:161], v[20:23]
	v_mfma_f32_16x16x32_bf16 v[20:23], v[0:3], v[8:11], v[148:151]
	v_mfma_f32_16x16x32_bf16 v[8:11], v[214:217], v[8:11], v[174:177]
	v_mfma_f32_16x16x32_bf16 v[24:27], v[164:167], v[12:15], v[8:11]
	v_mfma_f32_16x16x32_bf16 v[8:11], v[0:3], v[16:19], v[234:237]
	v_mfma_f32_16x16x32_bf16 v[28:31], v[4:7], v[12:15], v[20:23]
	v_mfma_f32_16x16x32_bf16 v[20:23], v[4:7], v[178:181], v[8:11]
	v_mfma_f32_16x16x32_bf16 v[8:11], v[214:217], v[16:19], v[186:189]
	v_mfma_f32_16x16x32_bf16 v[16:19], v[164:167], v[178:181], v[8:11]
	v_mfma_f32_16x16x32_bf16 v[8:11], v[0:3], v[182:185], v[190:193]
	v_mfma_f32_16x16x32_bf16 v[0:3], v[0:3], v[238:241], v[128:131]
	v_mfma_f32_16x16x32_bf16 v[12:15], v[4:7], v[218:221], v[8:11]
	v_mfma_f32_16x16x32_bf16 v[8:11], v[214:217], v[182:185], v[194:197]
	v_mfma_f32_16x16x32_bf16 v[4:7], v[4:7], v[158:161], v[0:3]
	v_mfma_f32_16x16x32_bf16 v[0:3], v[214:217], v[238:241], v[140:143]
	v_mfma_f32_16x16x32_bf16 v[8:11], v[164:167], v[218:221], v[8:11]
	v_mfma_f32_16x16x32_bf16 v[0:3], v[164:167], v[158:161], v[0:3]
	v_lshlrev_b32_e32 v242, 2, v152
	v_and_b32_e32 v242, 0x7c, v242
	v_lshl_or_b32 v242, s51, 7, v242
	v_add_u32_e32 v243, 0x1600, v242
	v_mad_i64_i32 v[244:245], vcc, v243, 12, s[46:47]
	v_mad_i64_i32 v[246:247], vcc, v242, 12, s[46:47]
	global_load_dwordx4 v[218:221], v[244:245], off offset:16
	global_load_dwordx4 v[222:225], v[244:245], off offset:32
	global_load_dwordx4 v[226:229], v[244:245], off
	global_load_dwordx4 v[230:233], v[246:247], off offset:16
	global_load_dwordx4 v[234:237], v[246:247], off offset:32
	global_load_dwordx4 v[238:241], v[246:247], off
	s_movk_i32 s40, 0x100
	v_cmp_gt_u32_e32 vcc, s40, v152
	s_barrier
	s_and_saveexec_b64 s[40:41], vcc
	s_cbranch_execz .LBB0_1110
	s_barrier
; #define UFOR(v, n) _Pragma("unroll") for (int v = 0; v < (n); ++v)
; #define LDS_BARRIER() do { asm volatile("s_waitcnt lgkmcnt(0)" ::: "memory"); __builtin_amdgcn_s_barrier(); asm volatile("" ::: "memory"); } while (0)
; __device__ __forceinline__ unsigned pk2(float a, float b) { return (unsigned)f2bf(a) | ((unsigned)f2bf(b) << 16); }
; __device__ __forceinline__ float lo2f(unsigned u) { return __uint_as_float(u << 16); }
; __device__ __forceinline__ float hi2f(unsigned u) { return __uint_as_float(u & 0xffff0000u); }
; template <int EPI, int K, int KL> ...
;     ...
;     u16* U = (u16*)smem;
;     LDS_BARRIER();
;     UFOR(ai, 2) UFOR(bj, 2) UFOR(m, 4) {
;       const f32x4 a = acc[ai][bj][m][0], b = acc[ai][bj][m][1];
;       uint4 pk; pk.x = pk2(a[0], a[1]); pk.y = pk2(a[2], a[3]); pk.z = pk2(b[0], b[1]); pk.w = pk2(b[2], b[3]);
;       *(uint4*)(U + (ai * HALF + wr * 64 + m * 16 + fr) * 256 + bj * 128 + wc * 32 + fq * 8) = pk;
;     }
;     LDS_BARRIER();
;     {
;       const int c4 = (tid_ & 31) * 4, rb = tid_ >> 5;
;       const int gc = pn * 128 + c4;
;       float wg[4][3], wv[4][3];
;       UFOR(q, 4) UFOR(x, 3) { wg[q][x] = e.cw[(size_t)(gc + q) * 3 + x]; wv[q][x] = e.cw[(size_t)(DFF + gc + q) * 3 + x]; }
;       float pg[4], cgv[4], ng[4], pvv[4], cv[4], nv[4];
;       const int lr0 = rb * 16;
;       {
;         const int lrp = lr0 > 0 ? lr0 - 1 : 0;
;         const uint2 a = *(const uint2*)(U + lrp * 256 + c4), b = *(const uint2*)(U + lrp * 256 + 128 + c4);
;         pg[0] = lo2f(a.x); pg[1] = hi2f(a.x); pg[2] = lo2f(a.y); pg[3] = hi2f(a.y);
;         pvv[0] = lo2f(b.x); pvv[1] = hi2f(b.x); pvv[2] = lo2f(b.y); pvv[3] = hi2f(b.y);
;         const uint2 c = *(const uint2*)(U + lr0 * 256 + c4), d = *(const uint2*)(U + lr0 * 256 + 128 + c4);
;         cgv[0] = lo2f(c.x); cgv[1] = hi2f(c.x); cgv[2] = lo2f(c.y); cgv[3] = hi2f(c.y);
;         cv[0] = lo2f(d.x); cv[1] = hi2f(d.x); cv[2] = lo2f(d.y); cv[3] = hi2f(d.y);
;       }
.LBB0_1110:
	s_or_b64 exec, exec, s[40:41]
	v_bfe_u32 v128, v152, 4, 4
	v_xor_b32_e32 v128, v128, v154
	v_lshlrev_b32_e32 v128, 4, v128
	v_lshlrev_b32_e32 v129, 15, v153
	v_lshlrev_b32_e32 v130, 9, v154
	v_add3_u32 v128, v128, v129, v130
	v_cvt_pk_bf16_f32 v124, v124, v125
	v_cvt_pk_bf16_f32 v125, v126, v127
	v_cvt_pk_bf16_f32 v126, v120, v121
	v_cvt_pk_bf16_f32 v116, v116, v117
	v_cvt_pk_bf16_f32 v117, v118, v119
	v_cvt_pk_bf16_f32 v118, v112, v113
	v_cvt_pk_bf16_f32 v108, v108, v109
	v_cvt_pk_bf16_f32 v109, v110, v111
	v_cvt_pk_bf16_f32 v110, v104, v105
	v_cvt_pk_bf16_f32 v100, v100, v101
	v_cvt_pk_bf16_f32 v101, v102, v103
	v_cvt_pk_bf16_f32 v102, v96, v97
	v_cvt_pk_bf16_f32 v92, v92, v93
	v_cvt_pk_bf16_f32 v93, v94, v95
	v_cvt_pk_bf16_f32 v94, v88, v89
	v_cvt_pk_bf16_f32 v84, v84, v85
	v_cvt_pk_bf16_f32 v85, v86, v87
	v_cvt_pk_bf16_f32 v86, v80, v81
	v_cvt_pk_bf16_f32 v76, v76, v77
	v_cvt_pk_bf16_f32 v77, v78, v79
	v_cvt_pk_bf16_f32 v78, v72, v73
	v_cvt_pk_bf16_f32 v68, v68, v69
	v_cvt_pk_bf16_f32 v69, v70, v71
	v_cvt_pk_bf16_f32 v70, v64, v65
	v_cvt_pk_bf16_f32 v71, v66, v67
	v_cvt_pk_bf16_f32 v60, v60, v61
	v_cvt_pk_bf16_f32 v61, v62, v63
	v_cvt_pk_bf16_f32 v62, v56, v57
	v_cvt_pk_bf16_f32 v63, v58, v59
	v_cvt_pk_bf16_f32 v52, v52, v53
	v_cvt_pk_bf16_f32 v53, v54, v55
	v_cvt_pk_bf16_f32 v54, v48, v49
	v_cvt_pk_bf16_f32 v55, v50, v51
	v_cvt_pk_bf16_f32 v44, v44, v45
	v_cvt_pk_bf16_f32 v45, v46, v47
	v_cvt_pk_bf16_f32 v46, v40, v41
	v_cvt_pk_bf16_f32 v47, v42, v43
	v_cvt_pk_bf16_f32 v36, v36, v37
	v_cvt_pk_bf16_f32 v37, v38, v39
	v_cvt_pk_bf16_f32 v38, v32, v33
	v_cvt_pk_bf16_f32 v39, v34, v35
	v_cvt_pk_bf16_f32 v28, v28, v29
	v_cvt_pk_bf16_f32 v29, v30, v31
	v_cvt_pk_bf16_f32 v30, v24, v25
	v_cvt_pk_bf16_f32 v31, v26, v27
	v_cvt_pk_bf16_f32 v20, v20, v21
	v_cvt_pk_bf16_f32 v21, v22, v23
	v_cvt_pk_bf16_f32 v22, v16, v17
	v_cvt_pk_bf16_f32 v23, v18, v19
	v_cvt_pk_bf16_f32 v12, v12, v13
	v_cvt_pk_bf16_f32 v13, v14, v15
	v_cvt_pk_bf16_f32 v14, v8, v9
	v_cvt_pk_bf16_f32 v15, v10, v11
	v_cvt_pk_bf16_f32 v4, v4, v5
	v_cvt_pk_bf16_f32 v5, v6, v7
	v_cvt_pk_bf16_f32 v127, v122, v123
	v_cvt_pk_bf16_f32 v119, v114, v115
	v_cvt_pk_bf16_f32 v111, v106, v107
	v_cvt_pk_bf16_f32 v103, v98, v99
	v_cvt_pk_bf16_f32 v95, v90, v91
	v_cvt_pk_bf16_f32 v87, v82, v83
	v_cvt_pk_bf16_f32 v79, v74, v75
	v_cvt_pk_bf16_f32 v7, v2, v3
	v_cvt_pk_bf16_f32 v6, v0, v1
	v_add_u32_e32 v16, 0x14100, v128
	s_waitcnt lgkmcnt(0)
	s_barrier
	v_add_u32_e32 v32, 0x10100, v128
	ds_write_b128 v16, v[12:15]
	v_and_b32_e32 v16, 0x7c, v132
	v_add_u32_e32 v64, 0x10000, v128
	v_add_u32_e32 v56, 0x12000, v128
	v_add_u32_e32 v48, 0x14000, v128
	v_add_u32_e32 v40, 0x16000, v128
	ds_write_b128 v32, v[28:31]
	v_add_u32_e32 v24, 0x12100, v128
	v_add_u32_e32 v8, 0x16100, v128
	v_lshl_or_b32 v32, s51, 7, v16
	ds_write_b128 v128, v[124:127]
	ds_write_b128 v128, v[116:119] offset:8192
	ds_write_b128 v128, v[108:111] offset:16384
	ds_write_b128 v128, v[100:103] offset:24576
	ds_write_b128 v128, v[92:95] offset:256
	ds_write_b128 v128, v[84:87] offset:8448
	ds_write_b128 v128, v[76:79] offset:16640
	ds_write_b128 v128, v[68:71] offset:24832
	ds_write_b128 v64, v[60:63]
	ds_write_b128 v56, v[52:55]
	ds_write_b128 v48, v[44:47]
	ds_write_b128 v40, v[36:39]
	ds_write_b128 v24, v[20:23]
	ds_write_b128 v8, v[4:7]
	v_add_u32_e32 v0, 0x1600, v32
	s_waitcnt lgkmcnt(0)
	s_barrier
	s_waitcnt vmcnt(0)
	v_mov_b32_e32 v24, v218
	v_mov_b32_e32 v25, v219
	v_mov_b32_e32 v26, v220
	v_mov_b32_e32 v27, v221
	v_mov_b32_e32 v0, v222
	v_mov_b32_e32 v1, v223
	v_mov_b32_e32 v2, v224
	v_mov_b32_e32 v3, v225
	v_mov_b32_e32 v4, v226
	v_mov_b32_e32 v5, v227
	v_mov_b32_e32 v6, v228
	v_mov_b32_e32 v7, v229
	v_mov_b32_e32 v8, v230
	v_mov_b32_e32 v9, v231
	v_mov_b32_e32 v10, v232
	v_mov_b32_e32 v11, v233
	v_mov_b32_e32 v28, v234
	v_mov_b32_e32 v29, v235
	v_mov_b32_e32 v30, v236
	v_mov_b32_e32 v31, v237
	v_mov_b32_e32 v12, v238
	v_mov_b32_e32 v13, v239
	v_mov_b32_e32 v14, v240
	v_mov_b32_e32 v15, v241
	v_ashrrev_i32_e32 v34, 1, v152
	v_and_b32_e32 v132, -16, v34
	v_mov_b32_e32 v17, 0xffffff00
	v_lshl_add_u32 v17, v132, 8, v17
	v_cmp_lt_i32_e32 vcc, 15, v34
	v_lshl_add_u32 v64, v16, 1, 0
	v_bfe_u32 v96, v152, 1, 4
	v_and_b32_e32 v97, 1, v152
	v_lshlrev_b32_e32 v97, 3, v97
	s_ashr_i32 s51, s50, 31
	v_cndmask_b32_e32 v17, 0, v17, vcc
	v_lshrrev_b32_e32 v98, 8, v17
	v_and_b32_e32 v98, 15, v98
	v_xor_b32_e32 v98, v98, v96
	v_lshl_add_u32 v98, v98, 4, v97
	v_lshl_add_u32 v16, v17, 1, v98
	ds_read2_b64 v[16:19], v16 offset1:32
	s_ashr_i32 s53, s52, 31
	s_add_u32 s56, s52, -1
	s_addc_u32 s57, s53, -1
	s_add_i32 s61, s52, -1
	s_waitcnt lgkmcnt(0)
	v_and_b32_e32 v56, 0xffff0000, v16
	v_lshlrev_b32_e32 v58, 16, v16
	v_lshl_add_u32 v98, v96, 4, v97
	v_lshl_add_u32 v16, v132, 9, v98
	ds_read2_b64 v[20:23], v16 offset1:32
	s_ashr_i32 s62, s61, 31
	v_ashrrev_i32_e32 v33, 31, v32
	v_cmp_lt_i32_e64 s[40:41], -1, v34
	s_sub_u32 s58, s50, s42
	v_ashrrev_i32_e32 v35, 31, v132
	v_mov_b32_e32 v34, v132
	s_waitcnt lgkmcnt(0)
	v_lshlrev_b32_e32 v47, 16, v21
	v_lshlrev_b32_e32 v46, 16, v20
	v_and_b32_e32 v45, 0xffff0000, v21
	v_and_b32_e32 v44, 0xffff0000, v20
	v_lshlrev_b32_e32 v50, 16, v22
	v_lshlrev_b32_e32 v51, 16, v23
	v_and_b32_e32 v49, 0xffff0000, v23
	v_and_b32_e32 v48, 0xffff0000, v22
	s_subb_u32 s59, s51, s43
	s_movk_i32 s63, 0x2c00
	v_lshlrev_b32_e32 v63, 16, v19
	v_lshlrev_b32_e32 v62, 16, v18
	v_and_b32_e32 v61, 0xffff0000, v19
	v_and_b32_e32 v60, 0xffff0000, v18
	v_and_b32_e32 v57, 0xffff0000, v17
	v_lshlrev_b32_e32 v59, 16, v17
	v_mov_b32_e32 v248, 0x3a27c5ac
	s_waitcnt vmcnt(0)
	v_mov_b32_e32 v16, v24
	v_mov_b32_e32 v20, v9
	v_mov_b32_e32 v21, v31
	v_mov_b32_e32 v9, v30
	v_mov_b32_e32 v22, v15
	v_mov_b32_e32 v23, v29
	v_mov_b32_e32 v15, v28
	v_lshl_add_u64 v[28:29], s[42:43], 0, v[34:35]
	v_lshlrev_b64 v[30:31], 1, v[32:33]
	v_mov_b32_e32 v18, v7
	v_mov_b32_e32 v19, v1
	v_mov_b32_e32 v7, v0
	v_mov_b32_e32 v0, v13
	v_mov_b32_e32 v1, v11
	v_mov_b32_e32 v13, v10
	v_mov_b32_e32 v11, s59
	v_sub_co_u32_e32 v10, vcc, s58, v132
	v_mad_u64_u32 v[30:31], s[58:59], v28, s63, v[30:31]
	v_mov_b32_e32 v32, v31
	s_sub_u32 s42, s61, s42
	v_subb_co_u32_e32 v11, vcc, v11, v35, vcc
	v_mad_u64_u32 v[32:33], s[58:59], v29, s63, v[32:33]
	s_subb_u32 s43, s62, s43
	v_mov_b32_e32 v31, v32
	v_readlane_b32 s58, v254, 38
	v_mov_b32_e32 v33, s43
	v_sub_co_u32_e32 v32, vcc, s42, v132
	v_readlane_b32 s59, v254, 39
	s_nop 0
	v_subb_co_u32_e32 v33, vcc, v33, v35, vcc
	v_mov_b32_e32 v17, v2
	v_mov_b32_e32 v2, v25
	v_mov_b32_e32 v24, v5
	v_mov_b32_e32 v25, v27
	v_mov_b32_e32 v5, v26
	v_lshl_add_u64 v[26:27], v[10:11], 0, -1
	v_lshl_add_u64 v[30:31], s[58:59], 0, v[30:31]
	v_lshl_add_u64 v[34:35], v[32:33], 0, -1
	s_mov_b64 s[58:59], 0
	s_branch .LBB0_1112
